# norm1 prologue: 24 dependent load/wait/ds_write rounds replaced by 24 loads in flight (code placed out of line so all other code keeps its address)
# speedup vs baseline: 1.0024x; 1.0024x over previous
; __device__ __forceinline__ void phase_norm(const Params& p, unsigned char* lds, const float* __restrict__ xin, const float* g, const float* mod  , int shift_off, int scale_off, bf16_t* __restrict__ hout, const float* wsc  , float* scal) {
;     ...
;     if (wsc) { for (int i = tid; i < 12 * DM; i += NTHR) wl[i] = wsc[i]; __syncthreads(); }
.LBB0_752:
	s_waitcnt vmcnt(0)
	v_mov_b32_e32 v2, v212
	s_movk_i32 s0, 0x3000
	s_nop 0
	v_cmp_gt_i32_e32 vcc, s0, v2
	s_and_saveexec_b64 s[0:1], vcc
	s_cbranch_execz .LBB0_755
	s_branch .Ln1_new
	s_nop 0
	s_nop 0
	s_nop 0
	s_nop 0
	s_nop 0
	s_nop 0
	s_nop 0
	s_nop 0
	s_nop 0
	s_nop 0
	s_nop 0
	s_nop 0
	s_nop 0
	s_nop 0
	s_nop 0
	s_nop 0
	s_nop 0
	s_nop 0
	s_nop 0
	s_nop 0
	s_nop 0
	s_nop 0
	s_nop 0
	s_nop 0
	s_nop 0
	s_nop 0
	s_nop 0
	s_nop 0
	s_nop 0
	s_nop 0
	s_nop 0
	s_nop 0
	s_nop 0
	s_nop 0
	s_nop 0
	s_nop 0
	s_nop 0

; __device__ __forceinline__ void phase_norm(const Params& p, unsigned char* lds, const float* __restrict__ xin, const float* g, const float* mod  , int shift_off, int scale_off, bf16_t* __restrict__ hout, const float* wsc  , float* scal) {
;     ...
;     if (wsc) { for (int i = tid; i < 12 * DM; i += NTHR) wl[i] = wsc[i]; __syncthreads(); }
.Ln1_new:
	v_readlane_b32 s2, v255, 3
	s_nop 0
	s_mul_hi_i32 s3, s2, 0xc000
	s_mul_i32 s2, s2, 0xc000
	s_add_u32 s2, s86, s2
	s_addc_u32 s3, s87, s3
	s_add_u32 s2, s2, 0x31000
	s_addc_u32 s3, s3, 0
	v_lshlrev_b32_e32 v6, 2, v2
	global_load_dword v10, v6, s[2:3]
	global_load_dword v11, v6, s[2:3] offset:2048
	s_add_u32 s2, s2, 0x1000
	s_addc_u32 s3, s3, 0
	global_load_dword v12, v6, s[2:3]
	global_load_dword v13, v6, s[2:3] offset:2048
	s_add_u32 s2, s2, 0x1000
	s_addc_u32 s3, s3, 0
	global_load_dword v14, v6, s[2:3]
	global_load_dword v15, v6, s[2:3] offset:2048
	s_add_u32 s2, s2, 0x1000
	s_addc_u32 s3, s3, 0
	global_load_dword v16, v6, s[2:3]
	global_load_dword v17, v6, s[2:3] offset:2048
	s_add_u32 s2, s2, 0x1000
	s_addc_u32 s3, s3, 0
	global_load_dword v18, v6, s[2:3]
	global_load_dword v19, v6, s[2:3] offset:2048
	s_add_u32 s2, s2, 0x1000
	s_addc_u32 s3, s3, 0
	global_load_dword v20, v6, s[2:3]
	global_load_dword v21, v6, s[2:3] offset:2048
	s_add_u32 s2, s2, 0x1000
	s_addc_u32 s3, s3, 0
	global_load_dword v22, v6, s[2:3]
	global_load_dword v23, v6, s[2:3] offset:2048
	s_add_u32 s2, s2, 0x1000
	s_addc_u32 s3, s3, 0
	global_load_dword v24, v6, s[2:3]
	global_load_dword v25, v6, s[2:3] offset:2048
	s_add_u32 s2, s2, 0x1000
	s_addc_u32 s3, s3, 0
	global_load_dword v26, v6, s[2:3]
	global_load_dword v27, v6, s[2:3] offset:2048
	s_add_u32 s2, s2, 0x1000
	s_addc_u32 s3, s3, 0
	global_load_dword v28, v6, s[2:3]
	global_load_dword v29, v6, s[2:3] offset:2048
	s_add_u32 s2, s2, 0x1000
	s_addc_u32 s3, s3, 0
	global_load_dword v30, v6, s[2:3]
	global_load_dword v31, v6, s[2:3] offset:2048
	s_add_u32 s2, s2, 0x1000
	s_addc_u32 s3, s3, 0
	global_load_dword v32, v6, s[2:3]
	global_load_dword v33, v6, s[2:3] offset:2048
	s_waitcnt vmcnt(23)
	ds_write_b32 v6, v10
	s_waitcnt vmcnt(22)
	ds_write_b32 v6, v11 offset:2048
	s_waitcnt vmcnt(21)
	ds_write_b32 v6, v12 offset:4096
	s_waitcnt vmcnt(20)
	ds_write_b32 v6, v13 offset:6144
	s_waitcnt vmcnt(19)
	ds_write_b32 v6, v14 offset:8192
	s_waitcnt vmcnt(18)
	ds_write_b32 v6, v15 offset:10240
	s_waitcnt vmcnt(17)
	ds_write_b32 v6, v16 offset:12288
	s_waitcnt vmcnt(16)
	ds_write_b32 v6, v17 offset:14336
	s_waitcnt vmcnt(15)
	ds_write_b32 v6, v18 offset:16384
	s_waitcnt vmcnt(14)
	ds_write_b32 v6, v19 offset:18432
	s_waitcnt vmcnt(13)
	ds_write_b32 v6, v20 offset:20480
	s_waitcnt vmcnt(12)
	ds_write_b32 v6, v21 offset:22528
	s_waitcnt vmcnt(11)
	ds_write_b32 v6, v22 offset:24576
	s_waitcnt vmcnt(10)
	ds_write_b32 v6, v23 offset:26624
	s_waitcnt vmcnt(9)
	ds_write_b32 v6, v24 offset:28672
	s_waitcnt vmcnt(8)
	ds_write_b32 v6, v25 offset:30720
	s_waitcnt vmcnt(7)
	ds_write_b32 v6, v26 offset:32768
	s_waitcnt vmcnt(6)
	ds_write_b32 v6, v27 offset:34816
	s_waitcnt vmcnt(5)
	ds_write_b32 v6, v28 offset:36864
	s_waitcnt vmcnt(4)
	ds_write_b32 v6, v29 offset:38912
	s_waitcnt vmcnt(3)
	ds_write_b32 v6, v30 offset:40960
	s_waitcnt vmcnt(2)
	ds_write_b32 v6, v31 offset:43008
	s_waitcnt vmcnt(1)
	ds_write_b32 v6, v32 offset:45056
	s_waitcnt vmcnt(0)
	ds_write_b32 v6, v33 offset:47104
	s_branch .LBB0_755
